# P2 staging: the sample's new K/V row loads issued together with the sixteen tile loads (one serialized round trip less before the staging barrier)
# baseline (speedup 1.0000x reference)
; #define LAS __attribute__((address_space(3)))
; template <class T, class P> __device__ __forceinline__ void gst_nt(P p, T v) { __builtin_nontemporal_store(v, (GAS T*)p); }
; template <class T, class P> __device__ __forceinline__ T gld_nt(P p) { return __builtin_nontemporal_load((GAS const T*)p); }
; __device__ __forceinline__ u32x2 pk4(f32x4 a) { u32x2 w; w.x = pk2(a[0], a[1]); w.y = pk2(a[2], a[3]); return w; }
; __device__ __forceinline__ void p2_phase(LAS unsigned char* lds, const int L, const int w0) {
;     ...
;                 if (kp >= 0) { const size_t r = (size_t)(b * 2048 + kp); kv[it] = gld<u32x4>(A.K + r * 128 + kvh * 64 + ch * 8); vv[it] = gld<u32x4>(A.V + r * 128 + kvh * 64 + ch * 8); }
;                 const int j = idx >> 4, c16 = idx & 15;
;                 kq[it] = gld_nt<f32x4>(A.cache_k + cb + (size_t)j * 128 + c16 * 4); vq[it] = gld_nt<f32x4>(A.cache_v + cb + (size_t)j * 128 + c16 * 4);
;             }
; #pragma unroll
;             for (int it = 0; it < 4; ++it) {
;                 const int idx = it * 512 + tid, kj = idx >> 3, ch = idx & 7;
;                 *(LAS u32x4*)(lds + kj * KSTR + ch * 16) = kv[it];
; #pragma unroll
;                 for (int e = 0; e < 8; ++e) { const unsigned w = vv[it][e >> 1]; vt[(ch * 8 + e) * (VSTR / 2) + kj] = (unsigned short)((e & 1) ? (w >> 16) : (w & 0xffffu)); }
;                 const int j = idx >> 4, c16 = idx & 15;
;                 *(LAS u32x2*)(lds + SK_OFF + j * KSTR + c16 * 8) = pk4(kq[it]);
;                 const u32x2 vw = pk4(vq[it]);
;                 svt[(c16 * 4 + 0) * (VSTR_S / 2) + j] = (unsigned short)(vw.x & 0xffffu); svt[(c16 * 4 + 1) * (VSTR_S / 2) + j] = (unsigned short)(vw.x >> 16);
;                 svt[(c16 * 4 + 2) * (VSTR_S / 2) + j] = (unsigned short)(vw.y & 0xffffu); svt[(c16 * 4 + 3) * (VSTR_S / 2) + j] = (unsigned short)(vw.y >> 16);
;                 if (j >= 4) { gst_nt<f32x4>(A.out + O_NKS + cb + (size_t)(j - 4) * 128 + c16 * 4, kq[it]); gst_nt<f32x4>(A.out + O_NVS + cb + (size_t)(j - 4) * 128 + c16 * 4, vq[it]); }
;             }
;             if (tid < 32) {
;                 const int t = tid >> 3, ch = tid & 7; const size_t r = (size_t)(NPR + 4 * sb + t);
;                 const u32x4 k4 = gld<u32x4>(A.K + r * 128 + kvh * 64 + ch * 8), v4 = gld<u32x4>(A.V + r * 128 + kvh * 64 + ch * 8);
.LBB0_658:
	s_or_b64 exec, exec, s[54:55]
	v_ashrrev_i32_e32 v70, 4, v65
	v_ashrrev_i32_e32 v71, 31, v70
	v_lshlrev_b64 v[72:73], 9, v[70:71]
	v_lshl_add_u64 v[56:57], v[60:61], 0, v[72:73]
	v_lshl_add_u64 v[60:61], v[62:63], 0, v[72:73]
	global_load_dwordx4 v[56:59], v[56:57], off nt
	v_and_b32_e32 v71, 15, v77
	global_load_dwordx4 v[60:63], v[60:61], off nt
	v_cmp_gt_i32_e32 vcc, 32, v77
	s_and_saveexec_b64 s[54:55], vcc
	s_cbranch_execz .Lp2h_skip
	v_add_u32_e32 v104, 0x4000, v79
	v_lshl_add_u32 v104, s68, 2, v104
	v_lshlrev_b32_e32 v104, 8, v104
	v_lshl_add_u32 v104, s50, 7, v104
	v_and_b32_e32 v105, 7, v77
	v_lshl_add_u32 v104, v105, 4, v104
	global_load_dwordx4 v[96:99], v104, s[14:15]
	global_load_dwordx4 v[100:103], v104, s[12:13]
.Lp2h_skip:
	s_or_b64 exec, exec, s[54:55]
	v_readlane_b32 s27, v255, 25
	v_and_b32_e32 v65, 7, v77
	s_waitcnt lgkmcnt(0)
	s_add_u32 s16, s58, s16
	v_lshl_add_u32 v76, v71, 3, s27
	v_readlane_b32 s27, v255, 26
	v_lshlrev_b32_e32 v67, 4, v65
	v_lshlrev_b32_e32 v192, 4, v71
	v_mov_b32_e32 v72, s27
	s_movk_i32 s27, 0x520
	s_addc_u32 s17, s59, s17
	v_add_u32_e32 v78, 0, v67
	v_mad_u32_u24 v83, v71, s27, v72
	v_lshl_add_u64 v[74:75], s[16:17], 0, v[192:193]
	s_mov_b64 s[16:17], 0x4620000
	v_mul_lo_u32 v71, v79, s23
	v_lshl_add_u64 v[72:73], v[74:75], 0, s[16:17]
	s_mov_b64 s[16:17], 0x6620000
	v_add_u32_e32 v84, v78, v71
	v_lshl_add_u64 v[74:75], v[74:75], 0, s[16:17]
	s_waitcnt vmcnt(9)
	ds_write_b128 v84, v[20:23]
	v_lshl_add_u32 v21, v79, 1, 0
	s_movk_i32 s16, 0x1040
	v_lshlrev_b32_e32 v69, 3, v65
	v_mad_u32_u24 v20, v65, s16, v21
	s_waitcnt vmcnt(8)
	ds_write_b16 v20, v16 offset:36864
	v_or_b32_e32 v20, 1, v69
	s_movk_i32 s16, 0x208
	v_mad_u32_u24 v21, v20, s16, v21
	ds_write_b16_d16_hi v21, v16 offset:36864
	ds_write_b16 v21, v17 offset:37384
	ds_write_b16_d16_hi v21, v17 offset:37904
	ds_write_b16 v21, v18 offset:38424
	ds_write_b16_d16_hi v21, v18 offset:38944
	ds_write_b16 v21, v19 offset:39464
	ds_write_b16_d16_hi v21, v19 offset:39984
	s_waitcnt vmcnt(7)
	v_cvt_pk_bf16_f32 v16, v24, v25
	v_mad_u64_u32 v[18:19], s[16:17], v64, s23, v[76:77]
	v_cvt_pk_bf16_f32 v17, v26, v27
	ds_write_b64 v18, v[16:17]
	s_waitcnt vmcnt(6)
	v_cvt_pk_bf16_f32 v16, v28, v29
	v_lshl_add_u32 v18, v64, 1, v83
	v_cmp_lt_i32_e32 vcc, 3, v64
	v_cvt_pk_bf16_f32 v17, v30, v31
	ds_write_b16 v18, v16
	ds_write_b16_d16_hi v18, v16 offset:328
	ds_write_b16 v18, v17 offset:656
	ds_write_b16_d16_hi v18, v17 offset:984
	s_and_saveexec_b64 s[16:17], vcc
	s_cbranch_execz .LBB0_660
	v_add_u32_e32 v192, -4, v64
	v_lshlrev_b64 v[16:17], 9, v[192:193]
	v_lshl_add_u64 v[18:19], v[74:75], 0, v[16:17]
	v_lshl_add_u64 v[16:17], v[72:73], 0, v[16:17]
	global_store_dwordx4 v[16:17], v[24:27], off nt
	global_store_dwordx4 v[18:19], v[28:31], off nt

; #define LAS __attribute__((address_space(3)))
; __device__ __forceinline__ void p2_phase(LAS unsigned char* lds, const int L, const int w0) {
;     ...
;             if (tid < 32) {
;                 const int t = tid >> 3, ch = tid & 7; const size_t r = (size_t)(NPR + 4 * sb + t);
;                 const u32x4 k4 = gld<u32x4>(A.K + r * 128 + kvh * 64 + ch * 8), v4 = gld<u32x4>(A.V + r * 128 + kvh * 64 + ch * 8);
;                 *(LAS u32x4*)(lds + SK_OFF + (128 + t) * KSTR + ch * 16) = k4;
; #pragma unroll
;                 for (int e = 0; e < 8; ++e) { const unsigned w = v4[e >> 1]; svt[(ch * 8 + e) * (VSTR_S / 2) + 128 + t] = (unsigned short)((e & 1) ? (w >> 16) : (w & 0xffffu)); }
;             }
.LBB0_666:
	s_or_b64 exec, exec, s[16:17]
	v_cmp_gt_i32_e32 vcc, 32, v77
	s_and_saveexec_b64 s[16:17], vcc
	s_cbranch_execz .LBB0_668
	s_lshl_b32 s27, s68, 2
	s_addk_i32 s27, 0x4000
	s_lshl_b32 s20, s20, 1
	v_lshlrev_b32_e32 v192, 1, v69
	v_readlane_b32 s12, v255, 25
	v_mul_u32_u24_e32 v9, 0xa40, v65
	v_lshlrev_b32_e32 v10, 1, v79
	v_add3_u32 v8, s12, v71, v67
	v_mul_u32_u24_e32 v11, 0x148, v20
	v_readlane_b32 s12, v255, 26
	s_nop 1
	v_add3_u32 v9, s12, v9, v10
	v_add3_u32 v10, s12, v11, v10
	s_waitcnt vmcnt(0)
	ds_write_b128 v8, v[96:99] offset:18432
	ds_write_b16 v9, v100 offset:256
	ds_write_b16_d16_hi v10, v100 offset:256
	ds_write_b16 v10, v101 offset:584
	ds_write_b16_d16_hi v10, v101 offset:912
	ds_write_b16 v10, v102 offset:1240
	ds_write_b16_d16_hi v10, v102 offset:1568
	ds_write_b16 v10, v103 offset:1896
	ds_write_b16_d16_hi v10, v103 offset:2224
